# DSA selection: candidate keys re-read with all LDS reads issued together and one wait instead of a per-group branch+read+wait ladder
# speedup vs baseline: 1.0058x; 1.0001x over previous
.LBB0_2398:
	s_waitcnt lgkmcnt(0)
	ds_read2st64_b32 v[2:3], v190 offset1:1
	ds_read_b32 v18, v190 offset:512
	ds_read_b32 v16, v190 offset:768
	ds_read_b32 v15, v190 offset:1024
	ds_read_b32 v14, v190 offset:1280
	ds_read_b32 v13, v190 offset:1536
	ds_read_b32 v12, v190 offset:1792
	ds_read_b32 v11, v190 offset:2048
	ds_read_b32 v10, v190 offset:2304
	ds_read_b32 v9, v190 offset:2560
	ds_read_b32 v8, v190 offset:2816
	ds_read_b32 v7, v190 offset:3072
	ds_read_b32 v6, v190 offset:3328
	ds_read_b32 v5, v190 offset:3584
	ds_read_b32 v4, v209
	v_mov_b32_e32 v0, 0
	s_waitcnt lgkmcnt(0)
	v_cmp_gt_u32_e64 s[90:91], s56, v196
	v_cmp_gt_u32_e64 s[92:93], s56, v197
	v_cmp_gt_u32_e64 s[94:95], s56, v198
	v_cmp_gt_u32_e64 s[96:97], s56, v199
	v_cndmask_b32_e64 v16, 0, v16, s[90:91]
	v_cndmask_b32_e64 v15, 0, v15, s[92:93]
	v_cndmask_b32_e64 v14, 0, v14, s[94:95]
	v_cndmask_b32_e64 v13, 0, v13, s[96:97]
	v_cmp_gt_u32_e64 s[90:91], s56, v200
	v_cmp_gt_u32_e64 s[92:93], s56, v201
	v_cmp_gt_u32_e64 s[94:95], s56, v202
	v_cmp_gt_u32_e64 s[96:97], s56, v203
	v_cndmask_b32_e64 v12, 0, v12, s[90:91]
	v_cndmask_b32_e64 v11, 0, v11, s[92:93]
	v_cndmask_b32_e64 v10, 0, v10, s[94:95]
	v_cndmask_b32_e64 v9, 0, v9, s[96:97]
	v_cmp_gt_u32_e64 s[90:91], s56, v204
	v_cmp_gt_u32_e64 s[92:93], s56, v205
	v_cmp_gt_u32_e64 s[94:95], s56, v206
	v_cmp_gt_u32_e64 s[96:97], s56, v207
	v_cndmask_b32_e64 v8, 0, v8, s[90:91]
	v_cndmask_b32_e64 v7, 0, v7, s[92:93]
	v_cndmask_b32_e64 v6, 0, v6, s[94:95]
	v_cndmask_b32_e64 v5, 0, v5, s[96:97]
	v_cmp_gt_u32_e64 s[90:91], s56, v208
	s_nop 1
	v_cndmask_b32_e64 v4, 0, v4, s[90:91]
